# MLA K/V prefetch addresses: scalar base stepped by SALU plus a loop-invariant per-lane offset (drops two 64-bit VALU multiply-adds per tile)
# speedup vs baseline: 1.0019x; 1.0019x over previous
; template <int MODE>
; __device__ __forceinline__ void attn_item(const Params& P, int layer, int b, int h, int map, int qb) {
;     ...
;   for (int s = 0; s < NST; ++s) qf[s] = qvalid ? *(const bf16x8*)(qp + (size_t)e_q * KLD + s * 16 + hh * 8) : (bf16x8){0, 0, 0, 0, 0, 0, 0, 0};
;   int tstart = 1, ntl;
;   if (meta) ntl = 1; else if (MODE == 2) { tstart = max(1, 4 * qb - 1); ntl = 4 * qb + 6 - tstart; } else ntl = 4 * qb + 5;
;   SM sa;
;   sa.m = NEG; sa.l = 0.f;
; #pragma unroll
;   for (int i = 0; i < 16; ++i) { sa.o0[i] = 0.f; sa.o1[i] = 0.f; }
;   if (MODE == 2) { sa.m = P.sinks[layer * 6 + h] * LOG2E; sa.l = hh == 0 ? 1.f : 0.f; }
;   float cfar = 0.f; if (MODE == 1) cfar = P.rel_bias[31 * 10 + bcol] * LOG2E;
;   struct Stage { u32x4 k[NLK], v; };
;   Stage stX, stY;
;   auto issue = [&](Stage& st, int t) {
; #pragma unroll
;     for (int u = 0; u < NLK; ++u) { int c = tid + 512 * u; if (c >= NKC) c -= (NKC % 512 == 0 ? 512 : NKC % 512);
;       const int row = c / CPR, cc = c % CPR; st.k[u] = *(const u32x4*)(kp + (size_t)(64 * t + row) * KLD + cc * 8); }
;     { const int row = tid >> 3, cc = tid & 7; st.v = *(const u32x4*)(vp + (size_t)row * E + 64 * t + cc * 8); }
;   };
;   auto commit = [&](const Stage& st, int bufi) {
; #pragma unroll
;     for (int u = 0; u < NLK; ++u) { int c = tid + 512 * u; if (c >= NKC) c -= (NKC % 512 == 0 ? 512 : NKC % 512);
;       const int row = c / CPR, cc = c % CPR; *(LAS u32x4*)(lds + bufi * KBUF + row * KSTR + cc * 16) = st.k[u]; }
;     { const int row = tid >> 3, cc = tid & 7; *(LAS u32x4*)(lds + 4 * KBUF + bufi * VBUF + row * 144 + cc * 16) = st.v; }
;   };
;   auto tile_of = [&](int i) { return i == 0 ? 0 : tstart + i - 1; };
;   auto skipf = [&](int t) { bool sk = !active; if (t > 0) { if (64 * t > eq0 + 31) sk = true; if (MODE == 2 && eq0 - (64 * t + 63) >= 128) sk = true; } return sk; };
;   const int pr = (r & 0x13) | ((r & 4) << 1) | ((r & 8) >> 1);
;   auto lookf = [&](int t) { return MODE != 0 && (t == 0 || MODE == 2 || (eq0 - (64 * t + 63) < 128)); };
;   auto qk = [&](f32x16& s0, f32x16& s1, float& boff, int bufi, int t) {
;     const ldsp_t kbuf = lds + bufi * KBUF;
;     __builtin_amdgcn_s_setprio(1);
;     boff = sa.m > -1e29f ? sa.m : 0.f;
;     const float init = ((MODE == 1 && !lookf(t)) ? cfar : 0.f) - boff;
; #pragma unroll
;     for (int q = 0; q < 16; ++q) { s0[q] = init; s1[q] = init; }
.LBB0_1306:
	s_or_b64 exec, exec, s[4:5]
	v_add_u32_e32 v2, 0xffffff00, v5
	v_cmp_lt_i32_e32 vcc, s94, v5
	v_ashrrev_i32_e32 v45, 3, v5
	s_lshl_b32 s90, s76, 1
	v_cndmask_b32_e32 v2, v5, v2, vcc
	v_mul_hi_i32 v3, v2, s55
	v_lshrrev_b32_e32 v7, 31, v3
	v_ashrrev_i32_e32 v3, 1, v3
	v_add_u32_e32 v180, v3, v7
	v_mul_lo_u32 v3, v180, 12
	v_sub_u32_e32 v7, v2, v3
	v_lshlrev_b32_e32 v10, 3, v7
	v_ashrrev_i32_e32 v11, 31, v10
	v_cmp_gt_i32_e32 vcc, s93, v5
	v_lshlrev_b64 v[32:33], 1, v[10:11]
	v_mov_b64_e32 v[2:3], s[70:71]
	v_cndmask_b32_e32 v10, v214, v219, vcc
	v_add_u32_e32 v10, v10, v5
	v_mul_hi_i32 v11, v10, s55
	v_lshrrev_b32_e32 v12, 31, v11
	v_ashrrev_i32_e32 v11, 1, v11
	v_add_u32_e32 v181, v11, v12
	v_mul_lo_u32 v11, v181, 12
	v_sub_u32_e32 v44, v10, v11
	v_lshlrev_b32_e32 v12, 3, v44
	v_ashrrev_i32_e32 v13, 31, v12
	v_mad_i64_i32 v[10:11], s[4:5], v181, s47, v[2:3]
	v_lshlrev_b64 v[34:35], 1, v[12:13]
	v_lshl_add_u64 v[16:17], v[10:11], 0, v[34:35]
	v_mov_b64_e32 v[10:11], s[44:45]
	v_mad_i64_i32 v[36:37], s[4:5], v45, s95, v[10:11]
	v_lshlrev_b32_e32 v10, 4, v5
	v_add_u32_e32 v18, s76, v180
	v_add_u32_e32 v24, s76, v181
	v_add_u32_e32 v40, s77, v180
	v_add_u32_e32 v42, s77, v181
	v_mad_i64_i32 v[8:9], s[4:5], v180, s47, v[2:3]
	v_and_b32_e32 v38, 0x70, v10
	v_mov_b32_e32 v39, v1
	v_mad_i64_i32 v[18:19], s[4:5], v18, s47, v[2:3]
	v_mad_i64_i32 v[24:25], s[4:5], v24, s47, v[2:3]
	v_lshl_add_u64 v[26:27], v[36:37], 0, s[90:91]
	v_mad_i64_i32 v[40:41], s[4:5], v40, s47, v[2:3]
	v_mad_i64_i32 v[42:43], s[4:5], v42, s47, v[2:3]
	v_lshl_add_u64 v[8:9], v[8:9], 0, v[32:33]
	v_lshl_add_u64 v[20:21], v[18:19], 0, v[32:33]
	v_lshl_add_u64 v[24:25], v[24:25], 0, v[34:35]
	v_lshl_add_u64 v[28:29], v[26:27], 0, v[38:39]
	v_lshl_add_u64 v[40:41], v[40:41], 0, v[32:33]
	v_lshl_add_u64 v[42:43], v[42:43], 0, v[34:35]
	s_lshl_b32 s90, s77, 1
	v_lshl_add_u64 v[148:149], v[36:37], 0, v[38:39]
	global_load_dwordx4 v[8:11], v[8:9], off
	s_nop 0
	global_load_dwordx4 v[12:15], v[148:149], off
	s_nop 0
	global_load_dwordx4 v[16:19], v[16:17], off
	s_nop 0
	global_load_dwordx4 v[20:23], v[20:21], off
	s_nop 0
	global_load_dwordx4 v[24:27], v[24:25], off
	s_nop 0
	global_load_dwordx4 v[28:31], v[28:29], off
	s_nop 0
	global_load_dwordx4 v[108:111], v[40:41], off
	global_load_dwordx4 v[104:107], v[42:43], off
	v_lshl_add_u64 v[40:41], v[36:37], 0, s[90:91]
	v_add_u32_e32 v42, s50, v180
	v_lshl_add_u64 v[40:41], v[40:41], 0, v[38:39]
	v_mad_i64_i32 v[42:43], s[4:5], v42, s47, v[2:3]
	v_lshl_add_u64 v[42:43], v[42:43], 0, v[32:33]
	global_load_dwordx4 v[112:115], v[40:41], off
	global_load_dwordx4 v[116:119], v[42:43], off
	v_add_u32_e32 v40, s50, v181
	v_mad_i64_i32 v[2:3], s[4:5], v40, s47, v[2:3]
	s_lshl_b32 s90, s50, 1
	v_lshl_add_u64 v[2:3], v[2:3], 0, v[34:35]
	v_lshl_add_u64 v[36:37], v[36:37], 0, s[90:91]
	v_lshl_add_u64 v[36:37], v[36:37], 0, v[38:39]
	global_load_dwordx4 v[120:123], v[2:3], off
	global_load_dwordx4 v[124:127], v[36:37], off
	v_and_b32_e32 v2, 19, v5
	v_lshlrev_b32_e32 v3, 1, v5
	v_lshrrev_b32_e32 v5, 1, v5
	v_lshlrev_b32_e32 v150, 3, v6
	v_and_b32_e32 v3, 8, v3
	v_and_b32_e32 v5, 4, v5
	v_mul_lo_u32 v182, v180, s89
	v_lshlrev_b32_e32 v183, 4, v7
	v_mul_lo_u32 v184, v181, s89
	v_lshlrev_b32_e32 v185, 4, v44
	v_mul_lo_u32 v6, v45, s54
	v_or3_b32 v2, v2, v3, v5
	v_add3_u32 v3, 0, v182, v183
	v_add3_u32 v5, 0, v184, v185
	v_add3_u32 v186, 0, v6, v38
	v_mul_u32_u24_e32 v2, 0xd0, v2
	s_or_b64 s[40:41], s[72:73], s[2:3]
	v_lshl_add_u64 v[152:153], s[70:71], 0, v[32:33]
	v_lshl_add_u64 v[166:167], s[70:71], 0, v[34:35]
	v_add3_u32 v188, 0, v2, v0
	v_mov_b32_e32 v2, v1
	v_mov_b32_e32 v6, v1
	v_mov_b32_e32 v7, v1
	v_mov_b32_e32 v187, 0xf149f2ca
	s_xor_b64 s[68:69], s[40:41], -1
	s_or_b32 s36, s21, 31
	s_mov_b32 s37, 0
	v_mov_b32_e32 v169, 0xf149f2ca
	v_mov_b32_e32 v192, 0
	v_mov_b32_e32 v193, 0
	v_mov_b32_e32 v194, 0
	v_mov_b32_e32 v195, 0
	v_mov_b32_e32 v196, 0
	v_mov_b32_e32 v197, 0
	v_mov_b32_e32 v198, 0
	v_mov_b32_e32 v199, 0
	v_mov_b32_e32 v200, 0
	v_mov_b32_e32 v201, 0
	v_mov_b32_e32 v202, 0
	v_mov_b32_e32 v203, 0
	v_mov_b32_e32 v204, 0
	v_mov_b32_e32 v205, 0
	v_mov_b32_e32 v206, 0
	v_mov_b32_e32 v207, 0
	v_mov_b32_e32 v190, 0
	s_mov_b32 s42, 63
	s_waitcnt vmcnt(11)
	ds_write_b128 v3, v[8:11]
	s_waitcnt vmcnt(9)
	ds_write_b128 v5, v[16:19]
	ds_write_b128 v186, v[12:15] offset:53248
	s_waitcnt vmcnt(8)
	ds_write_b128 v3, v[20:23] offset:13312
	s_waitcnt vmcnt(7)
	ds_write_b128 v5, v[24:27] offset:13312
	s_waitcnt vmcnt(6)
	ds_write_b128 v186, v[28:31] offset:62464
	v_mul_u32_u24_e32 v3, 0x90, v4
	v_mov_b32_e32 v14, v1
	v_mov_b32_e32 v15, v1
	v_add3_u32 v189, 0, v3, v0
	v_mov_b32_e32 v0, v1
	v_mov_b32_e32 v3, v1
	v_mov_b32_e32 v4, v1
	v_mov_b32_e32 v5, v1
	v_mov_b32_e32 v8, v1
	v_mov_b32_e32 v9, v1
	v_mov_b32_e32 v10, v1
	v_mov_b32_e32 v11, v1
	v_mov_b32_e32 v12, v1
	v_mov_b32_e32 v13, v1
	v_mov_b64_e32 v[30:31], v[14:15]
	v_mov_b64_e32 v[46:47], v[14:15]
	v_mov_b64_e32 v[28:29], v[12:13]
	v_mov_b64_e32 v[26:27], v[10:11]
	v_mov_b64_e32 v[24:25], v[8:9]
	v_mov_b64_e32 v[22:23], v[6:7]
	v_mov_b64_e32 v[20:21], v[4:5]
	v_mov_b64_e32 v[18:19], v[2:3]
	v_mov_b64_e32 v[16:17], v[0:1]
	v_mov_b64_e32 v[44:45], v[12:13]
	v_mov_b64_e32 v[42:43], v[10:11]
	v_mov_b64_e32 v[40:41], v[8:9]
	v_mov_b64_e32 v[38:39], v[6:7]
	v_mov_b64_e32 v[36:37], v[4:5]
	v_mov_b64_e32 v[34:35], v[2:3]
	v_mov_b64_e32 v[32:33], v[0:1]
	s_waitcnt lgkmcnt(0)
	s_barrier
	v_subrev_u32_e32 v208, s70, v152
	v_subrev_u32_e32 v209, s70, v166
	v_subrev_u32_e32 v191, s44, v148
	v_mad_u32_u24 v208, v180, s47, v208
	v_mad_u32_u24 v209, v181, s47, v209
	s_branch .LBB0_1309

; #define LAS __attribute__((address_space(3)))
; template <int MODE>
; __device__ __forceinline__ void attn_item(const Params& P, int layer, int b, int h, int map, int qb) {
;     ...
;   auto issue = [&](Stage& st, int t) {
; #pragma unroll
;     for (int u = 0; u < NLK; ++u) { int c = tid + 512 * u; if (c >= NKC) c -= (NKC % 512 == 0 ? 512 : NKC % 512);
;       const int row = c / CPR, cc = c % CPR; st.k[u] = *(const u32x4*)(kp + (size_t)(64 * t + row) * KLD + cc * 8); }
;     { const int row = tid >> 3, cc = tid & 7; st.v = *(const u32x4*)(vp + (size_t)row * E + 64 * t + cc * 8); }
;   };
;   auto commit = [&](const Stage& st, int bufi) {
; #pragma unroll
;     for (int u = 0; u < NLK; ++u) { int c = tid + 512 * u; if (c >= NKC) c -= (NKC % 512 == 0 ? 512 : NKC % 512);
;       const int row = c / CPR, cc = c % CPR; *(LAS u32x4*)(lds + bufi * KBUF + row * KSTR + cc * 16) = st.k[u]; }
;     { const int row = tid >> 3, cc = tid & 7; *(LAS u32x4*)(lds + 4 * KBUF + bufi * VBUF + row * 144 + cc * 16) = st.v; }
.LBB0_1308:
	s_xor_b32 s2, s43, 3
	s_mul_i32 s3, s2, 0x3400
	s_add_i32 s3, s3, 0
	v_add3_u32 v0, s3, v182, v183
	s_waitcnt vmcnt(5)
	ds_write_b128 v0, v[116:119]
	v_add3_u32 v0, s3, v184, v185
	s_mulk_i32 s2, 0x2400
	s_waitcnt vmcnt(4)
	ds_write_b128 v0, v[120:123]
	v_add_u32_e32 v0, s2, v186
	s_add_i32 s2, s37, 5
	s_min_i32 s2, s2, s63
	s_lshl_b32 s90, s2, 6
	s_waitcnt vmcnt(3)
	ds_write_b128 v0, v[124:127] offset:53248
	s_mul_i32 s2, s90, s47
	s_add_u32 s98, s70, s2
	s_addc_u32 s99, s71, 0
	global_load_dwordx4 v[116:119], v208, s[98:99]
	global_load_dwordx4 v[120:123], v209, s[98:99]
	s_lshl_b32 s2, s90, 1
	s_add_u32 s98, s44, s2
	s_addc_u32 s99, s45, 0
	global_load_dwordx4 v[124:127], v191, s[98:99]
	s_add_i32 s37, s37, 2
	s_addk_i32 s42, 0x80
	s_cmp_gt_u32 s37, s62
	s_waitcnt lgkmcnt(0)
	s_barrier
	s_cbranch_scc1 .LBB0_1322

; #define LAS __attribute__((address_space(3)))
; template <int MODE>
; __device__ __forceinline__ void attn_item(const Params& P, int layer, int b, int h, int map, int qb) {
;     ...
;   auto issue = [&](Stage& st, int t) {
; #pragma unroll
;     for (int u = 0; u < NLK; ++u) { int c = tid + 512 * u; if (c >= NKC) c -= (NKC % 512 == 0 ? 512 : NKC % 512);
;       const int row = c / CPR, cc = c % CPR; st.k[u] = *(const u32x4*)(kp + (size_t)(64 * t + row) * KLD + cc * 8); }
;     { const int row = tid >> 3, cc = tid & 7; st.v = *(const u32x4*)(vp + (size_t)row * E + 64 * t + cc * 8); }
;   };
;   auto commit = [&](const Stage& st, int bufi) {
; #pragma unroll
;     for (int u = 0; u < NLK; ++u) { int c = tid + 512 * u; if (c >= NKC) c -= (NKC % 512 == 0 ? 512 : NKC % 512);
;       const int row = c / CPR, cc = c % CPR; *(LAS u32x4*)(lds + bufi * KBUF + row * KSTR + cc * 16) = st.k[u]; }
;     { const int row = tid >> 3, cc = tid & 7; *(LAS u32x4*)(lds + 4 * KBUF + bufi * VBUF + row * 144 + cc * 16) = st.v; }
;   };
;   auto tile_of = [&](int i) { return i == 0 ? 0 : tstart + i - 1; };
;   auto skipf = [&](int t) { bool sk = !active; if (t > 0) { if (64 * t > eq0 + 31) sk = true; if (MODE == 2 && eq0 - (64 * t + 63) >= 128) sk = true; } return sk; };
;   const int pr = (r & 0x13) | ((r & 4) << 1) | ((r & 8) >> 1);
;   auto lookf = [&](int t) { return MODE != 0 && (t == 0 || MODE == 2 || (eq0 - (64 * t + 63) < 128)); };
;   auto qk = [&](f32x16& s0, f32x16& s1, float& boff, int bufi, int t) {
;     const ldsp_t kbuf = lds + bufi * KBUF;
;     __builtin_amdgcn_s_setprio(1);
;     boff = sa.m > -1e29f ? sa.m : 0.f;
;     const float init = ((MODE == 1 && !lookf(t)) ? cfar : 0.f) - boff;
; #pragma unroll
;     for (int q = 0; q < 16; ++q) { s0[q] = init; s1[q] = init; }
; #pragma unroll
;     for (int s = 0; s < NST; ++s) {
;       const bf16x8 a0 = *(LAS const bf16x8*)(kbuf + pr * KSTR + s * 32 + hh * 16);
;       const bf16x8 a1 = *(LAS const bf16x8*)(kbuf + (32 + pr) * KSTR + s * 32 + hh * 16);
;       s0 = __builtin_amdgcn_mfma_f32_32x32x16_bf16(a0, qf[s], s0, 0, 0, 0);
;       s1 = __builtin_amdgcn_mfma_f32_32x32x16_bf16(a1, qf[s], s1, 0, 0, 0);
;     }
;     __builtin_amdgcn_sched_group_barrier(0x100, 4, 0);
; #pragma unroll
;     for (int s = 0; s < NST - 2; ++s) { __builtin_amdgcn_sched_group_barrier(0x8, 2, 0); __builtin_amdgcn_sched_group_barrier(0x100, 2, 0); }
.LBB0_1316:
	s_xor_b32 s2, s43, 2
	s_mul_i32 s3, s2, 0x3400
	s_add_i32 s3, s3, 0
	v_add3_u32 v0, s3, v182, v183
	s_waitcnt vmcnt(5)
	ds_write_b128 v0, v[108:111]
	v_add3_u32 v0, s3, v184, v185
	s_mulk_i32 s2, 0x2400
	s_waitcnt vmcnt(4)
	ds_write_b128 v0, v[104:107]
	v_add_u32_e32 v0, s2, v186
	s_add_i32 s2, s37, 4
	s_min_i32 s2, s2, s63
	s_lshl_b32 s90, s2, 6
	s_waitcnt vmcnt(3)
	ds_write_b128 v0, v[112:115] offset:53248
	s_mul_i32 s2, s90, s47
	s_add_u32 s98, s70, s2
	s_addc_u32 s99, s71, 0
	global_load_dwordx4 v[108:111], v208, s[98:99]
	global_load_dwordx4 v[104:107], v209, s[98:99]
	s_lshl_b32 s2, s90, 1
	s_add_u32 s98, s44, s2
	s_addc_u32 s99, s45, 0
	global_load_dwordx4 v[112:115], v191, s[98:99]
	s_add_i32 s2, s37, 1
	s_cmp_ge_u32 s2, s62
	s_cbranch_scc1 .LBB0_1308
	s_add_i32 s2, s42, 1
	s_cmp_le_i32 s2, s36
	s_cselect_b64 s[2:3], -1, 0
	s_and_b64 s[2:3], s[2:3], s[40:41]
	s_andn2_b64 vcc, exec, s[2:3]
	s_cbranch_vccnz .LBB0_1308
	s_add_i32 s3, s42, 64
	s_or_b32 s2, s43, 1
	s_cmp_le_i32 s3, s21
	s_setprio 1
	s_mul_i32 s3, s2, 0x3400
	v_add_u32_e32 v0, s3, v188
	ds_read_b128 v[6:9], v0
	ds_read_b128 v[2:5], v0 offset:6656
	ds_read_b128 v[10:13], v0 offset:32
	ds_read_b128 v[128:131], v0 offset:6688
	ds_read_b128 v[132:135], v0 offset:64
	ds_read_b128 v[136:139], v0 offset:6720
	ds_read_b128 v[140:143], v0 offset:96
	ds_read_b128 v[144:147], v0 offset:6752
	ds_read_b128 v[232:235], v0 offset:128
	ds_read_b128 v[236:239], v0 offset:6784
	ds_read_b128 v[240:243], v0 offset:160
	ds_read_b128 v[244:247], v0 offset:6816
	v_cmp_lt_f32_e32 vcc, s87, v169
	s_nop 1
	v_cndmask_b32_e32 v168, 0, v169, vcc
	s_waitcnt lgkmcnt(11)
	s_nop 0
	v_mfma_f32_32x32x16_bf16 v[64:79], v[6:9], v[84:87], v[192:207]
	s_waitcnt lgkmcnt(10)
	v_mfma_f32_32x32x16_bf16 v[48:63], v[2:5], v[84:87], v[192:207]
	s_waitcnt lgkmcnt(9)
	v_mfma_f32_32x32x16_bf16 v[64:79], v[10:13], v[80:83], v[64:79]
	s_waitcnt lgkmcnt(8)
	v_mfma_f32_32x32x16_bf16 v[48:63], v[128:131], v[80:83], v[48:63]
	s_waitcnt lgkmcnt(7)
	v_mfma_f32_32x32x16_bf16 v[64:79], v[132:135], v[92:95], v[64:79]
	s_waitcnt lgkmcnt(6)
	v_mfma_f32_32x32x16_bf16 v[48:63], v[136:139], v[92:95], v[48:63]
	s_waitcnt lgkmcnt(5)
	v_mfma_f32_32x32x16_bf16 v[64:79], v[140:143], v[88:91], v[64:79]
	s_waitcnt lgkmcnt(4)
	v_mfma_f32_32x32x16_bf16 v[48:63], v[144:147], v[88:91], v[48:63]
	s_waitcnt lgkmcnt(3)
	v_mfma_f32_32x32x16_bf16 v[64:79], v[232:235], v[100:103], v[64:79]
	s_waitcnt lgkmcnt(2)
	v_mfma_f32_32x32x16_bf16 v[48:63], v[236:239], v[100:103], v[48:63]
	s_waitcnt lgkmcnt(1)
	v_mfma_f32_32x32x16_bf16 v[64:79], v[240:243], v[96:99], v[64:79]
	s_waitcnt lgkmcnt(0)
	v_mfma_f32_32x32x16_bf16 v[48:63], v[244:247], v[96:99], v[48:63]
	s_setprio 0
	s_cbranch_scc1 .LBB0_1320
	v_add_u32_e32 v0, s42, v150
	v_add_u32_e32 v2, 1, v0
	v_add_u32_e32 v3, 33, v0
	v_cmp_gt_i32_e32 vcc, v2, v151
	s_nop 4
	v_cndmask_b32_e32 v64, v64, v187, vcc
	v_cmp_gt_i32_e32 vcc, v3, v151
	v_add_u32_e32 v3, 34, v0
	s_nop 0
	v_cndmask_b32_e32 v48, v48, v187, vcc
	v_cmp_lt_i32_e32 vcc, v2, v151
	v_add_u32_e32 v2, 3, v0
	s_nop 0
	v_cndmask_b32_e32 v65, v187, v65, vcc
	v_cmp_gt_i32_e32 vcc, v3, v151
	v_add_u32_e32 v3, 35, v0
	s_nop 0
	v_cndmask_b32_e32 v49, v49, v187, vcc
	v_cmp_gt_i32_e32 vcc, v2, v151
	v_add_u32_e32 v2, 4, v0
	s_nop 0
	v_cndmask_b32_e32 v66, v66, v187, vcc
	v_cmp_gt_i32_e32 vcc, v3, v151
	v_add_u32_e32 v3, 36, v0
	s_nop 0
	v_cndmask_b32_e32 v50, v50, v187, vcc
	v_cmp_gt_i32_e32 vcc, v2, v151
	v_add_u32_e32 v2, 5, v0
	s_nop 0
	v_cndmask_b32_e32 v67, v67, v187, vcc
	v_cmp_gt_i32_e32 vcc, v3, v151
	v_add_u32_e32 v3, 37, v0
	s_nop 0
	v_cndmask_b32_e32 v51, v51, v187, vcc
	v_cmp_gt_i32_e32 vcc, v2, v151
	v_add_u32_e32 v2, 6, v0
	s_nop 0
	v_cndmask_b32_e32 v68, v68, v187, vcc
	v_cmp_gt_i32_e32 vcc, v3, v151
	v_add_u32_e32 v3, 38, v0
	s_nop 0
	v_cndmask_b32_e32 v52, v52, v187, vcc
	v_cmp_gt_i32_e32 vcc, v2, v151
	v_add_u32_e32 v2, 7, v0
	s_nop 0
	v_cndmask_b32_e32 v69, v69, v187, vcc
	v_cmp_gt_i32_e32 vcc, v3, v151
	v_add_u32_e32 v3, 39, v0
	s_nop 0
	v_cndmask_b32_e32 v53, v53, v187, vcc
	v_cmp_gt_i32_e32 vcc, v2, v151
	v_add_u32_e32 v2, 8, v0
	s_nop 0
	v_cndmask_b32_e32 v70, v70, v187, vcc
	v_cmp_gt_i32_e32 vcc, v3, v151
	v_add_u32_e32 v3, 40, v0
	s_nop 0
	v_cndmask_b32_e32 v54, v54, v187, vcc
	v_cmp_gt_i32_e32 vcc, v2, v151
	v_add_u32_e32 v2, 17, v0
	s_nop 0
	v_cndmask_b32_e32 v71, v71, v187, vcc
	v_cmp_gt_i32_e32 vcc, v3, v151
	v_add_u32_e32 v3, 49, v0
	s_nop 0
	v_cndmask_b32_e32 v55, v55, v187, vcc
	v_cmp_gt_i32_e32 vcc, v2, v151
	v_add_u32_e32 v2, 18, v0
	s_nop 0
	v_cndmask_b32_e32 v72, v72, v187, vcc
	v_cmp_gt_i32_e32 vcc, v3, v151
	v_add_u32_e32 v3, 50, v0
	s_nop 0
	v_cndmask_b32_e32 v56, v56, v187, vcc
	v_cmp_gt_i32_e32 vcc, v2, v151
	v_add_u32_e32 v2, 19, v0
	s_nop 0
	v_cndmask_b32_e32 v73, v73, v187, vcc
	v_cmp_gt_i32_e32 vcc, v3, v151
	v_add_u32_e32 v3, 51, v0
	s_nop 0
	v_cndmask_b32_e32 v57, v57, v187, vcc
	v_cmp_gt_i32_e32 vcc, v2, v151
	v_add_u32_e32 v2, 20, v0
	s_nop 0
	v_cndmask_b32_e32 v74, v74, v187, vcc
	v_cmp_gt_i32_e32 vcc, v3, v151
	v_add_u32_e32 v3, 52, v0
	s_nop 0
	v_cndmask_b32_e32 v58, v58, v187, vcc
	v_cmp_gt_i32_e32 vcc, v2, v151
	v_add_u32_e32 v2, 21, v0
	s_nop 0
	v_cndmask_b32_e32 v75, v75, v187, vcc
	v_cmp_gt_i32_e32 vcc, v3, v151
	v_add_u32_e32 v3, 53, v0
	s_nop 0
	v_cndmask_b32_e32 v59, v59, v187, vcc
	v_cmp_gt_i32_e32 vcc, v2, v151
	v_add_u32_e32 v2, 22, v0
	s_nop 0
	v_cndmask_b32_e32 v76, v76, v187, vcc
	v_cmp_gt_i32_e32 vcc, v3, v151
	v_add_u32_e32 v3, 54, v0
	s_nop 0
	v_cndmask_b32_e32 v60, v60, v187, vcc
	v_cmp_gt_i32_e32 vcc, v2, v151
	v_add_u32_e32 v2, 23, v0
	s_nop 0
	v_cndmask_b32_e32 v77, v77, v187, vcc
	v_cmp_gt_i32_e32 vcc, v3, v151
	v_add_u32_e32 v3, 55, v0
	s_nop 0
	v_cndmask_b32_e32 v61, v61, v187, vcc
	v_cmp_gt_i32_e32 vcc, v2, v151
	v_add_u32_e32 v2, 24, v0
	v_add_u32_e32 v0, 56, v0
	v_cndmask_b32_e32 v78, v78, v187, vcc
	v_cmp_gt_i32_e32 vcc, v3, v151
	s_nop 1
	v_cndmask_b32_e32 v62, v62, v187, vcc
	v_cmp_gt_i32_e32 vcc, v2, v151
	s_nop 1
	v_cndmask_b32_e32 v79, v79, v187, vcc
	v_cmp_gt_i32_e32 vcc, v0, v151
	s_nop 1
	v_cndmask_b32_e32 v63, v63, v187, vcc
